# MLP down GEMM: tile groups 4 row-tiles x 8 col-tiles (was 8x8) so each XCD streams every A panel (H) once per round instead of twice
# speedup vs baseline: 1.0077x; 1.0077x over previous
.LBB0_1222:
	v_readlane_b32 s0, v254, 0
	v_readlane_b32 s1, v254, 1
	v_readlane_b32 s2, v254, 4
	v_mbcnt_lo_u32_b32 v0, -1, 0
	v_mbcnt_hi_u32_b32 v0, -1, v0
	s_mov_b32 s19, s80
	v_readlane_b32 s2, v254, 5
	v_readlane_b32 s3, v254, 6
	s_waitcnt vmcnt(0)
	v_mov_b64_e32 v[2:3], s[0:1]
	s_load_dword s18, s[2:3], 0x0
	flat_load_dwordx4 v[2:5], v[2:3] offset:216
	v_readlane_b32 s0, v254, 22
	s_cmp_eq_u32 s0, 3
	s_mov_b64 s[0:1], 0x4200000
	s_waitcnt vmcnt(0) lgkmcnt(0)
	v_lshl_add_u64 v[198:199], v[4:5], 0, s[0:1]
	s_mov_b64 s[0:1], 0x8200000
	v_lshl_add_u64 v[200:201], v[4:5], 0, s[0:1]
	s_mov_b64 s[0:1], 0x12200000
	v_lshl_add_u64 v[202:203], v[4:5], 0, s[0:1]
	s_mov_b64 s[0:1], -1
	s_cbranch_scc1 .LBB0_1258
	v_mbcnt_lo_u32_b32 v0, -1, 0
	v_mbcnt_hi_u32_b32 v0, -1, v0
	s_cmpk_lt_i32 s19, 0x500
	v_add_u32_e32 v0, s81, v0
	s_cselect_b64 s[0:1], -1, 0
	s_cmpk_gt_i32 s19, 0x4ff
	v_readfirstlane_b32 s2, v0
	s_cbranch_scc1 .LBB0_1225
	s_ashr_i32 s3, s19, 31
	s_lshr_b32 s3, s3, 29
	s_add_i32 s3, s19, s3
	s_ashr_i32 s4, s3, 3
	s_and_b32 s3, s3, -8
	s_sub_i32 s3, s19, s3
	s_cmp_lt_i32 s3, 0
	s_movk_i32 s5, 0xa1
	s_cselect_b32 s5, s5, 0xa0
	s_mul_i32 s3, s3, s5
	s_add_i32 s3, s3, s4
	s_ashr_i32 s4, s3, 31
	s_lshr_b32 s4, s4, 26
	s_add_i32 s4, s3, s4
	s_ashr_i32 s5, s4, 5
	s_and_b32 s4, s4, 0xffe0
	s_sub_i32 s3, s3, s4
	s_bfe_i32 s4, s3, 0x80000
	s_bfe_u32 s4, s4, 0x3000c
	s_add_i32 s4, s3, s4
	s_bfe_i32 s6, s4, 0x80000
	s_and_b32 s4, s4, 0xfc
	s_sub_i32 s3, s3, s4
	s_lshl_b32 s5, s5, 2
	s_sext_i32_i16 s6, s6
	s_sext_i32_i8 s3, s3
	s_add_i32 s14, s5, s3
	s_ashr_i32 s12, s6, 2

.LBB0_1231:
	s_add_i32 s28, s28, 1
	s_mul_i32 s6, s28, s29
	s_mul_hi_u32 s7, s28, s18
	s_add_i32 s7, s7, s6
	s_mul_i32 s6, s28, s18
	s_add_u32 s16, s6, s19
	s_addc_u32 s17, s7, s30
	v_mov_b64_e32 v[136:137], 0x4ff
	v_cmp_gt_i64_e32 vcc, s[16:17], v[136:137]
	v_cmp_lt_i64_e64 s[6:7], s[16:17], v[242:243]
	s_cbranch_vccnz .LBB0_1233
	s_ashr_i32 s8, s16, 31
	s_lshr_b32 s8, s8, 29
	s_add_i32 s8, s16, s8
	s_ashr_i32 s9, s8, 3
	s_and_b32 s8, s8, -8
	s_sub_i32 s8, s16, s8
	s_cmp_lt_i32 s8, 0
	s_movk_i32 s10, 0xa1
	s_cselect_b32 s10, s10, 0xa0
	s_mul_i32 s8, s8, s10
	s_add_i32 s8, s8, s9
	s_ashr_i32 s9, s8, 31
	s_lshr_b32 s9, s9, 26
	s_add_i32 s9, s8, s9
	s_ashr_i32 s10, s9, 5
	s_lshl_b32 s10, s10, 2
	s_sub_i32 s11, 0xa0, s10
	s_min_i32 s11, s11, 4
	s_abs_i32 s13, s11
	v_cvt_f32_u32_e32 v0, s13
	s_sub_i32 s16, 0, s13
	s_andn2_b32 s9, s9, 31
	s_sub_i32 s9, s8, s9
	v_rcp_iflag_f32_e32 v0, v0
	s_abs_i32 s8, s9
	s_xor_b32 s15, s9, s11
	s_ashr_i32 s15, s15, 31
	v_mul_f32_e32 v0, 0x4f7ffffe, v0
	v_cvt_u32_f32_e32 v0, v0
	s_nop 0
	v_readfirstlane_b32 s17, v0
	s_mul_i32 s16, s16, s17
	s_mul_hi_u32 s16, s17, s16
	s_add_i32 s17, s17, s16
	s_mul_hi_u32 s16, s8, s17
	s_mul_i32 s17, s16, s13
	s_sub_i32 s8, s8, s17
	s_add_i32 s31, s16, 1
	s_sub_i32 s17, s8, s13
	s_cmp_ge_u32 s8, s13
	s_cselect_b32 s16, s31, s16
	s_cselect_b32 s8, s17, s8
	s_add_i32 s17, s16, 1
	s_cmp_ge_u32 s8, s13
	s_cselect_b32 s8, s17, s16
	s_xor_b32 s8, s8, s15
	s_sub_i32 s8, s8, s15
	s_mul_i32 s11, s8, s11
	s_sub_i32 s9, s9, s11
	s_add_i32 s10, s10, s9

.LBB0_1258:
	s_and_b64 vcc, exec, s[0:1]
	s_cbranch_vccz .LBB0_1275
	v_mbcnt_lo_u32_b32 v0, -1, 0
	v_mbcnt_hi_u32_b32 v0, -1, v0
	s_cmpk_gt_i32 s19, 0x4ff
	v_add_u32_e32 v0, s81, v0
	s_nop 0
	v_readfirstlane_b32 s3, v0
	s_cbranch_scc1 .LBB0_1275
	v_bfe_i32 v5, v0, 27, 1
	v_lshlrev_b32_e32 v4, 4, v0
	v_lshrrev_b32_e32 v5, 22, v5
	v_add_u32_e32 v5, v4, v5
	v_and_b32_e32 v5, 0xfffffc00, v5
	v_sub_u32_e32 v4, v4, v5
	v_lshrrev_b32_e32 v5, 4, v4
	v_ashrrev_i32_e32 v6, 31, v0
	v_bitop3_b32 v4, v5, v4, 32 bitop3:0x6c
	v_lshrrev_b32_e32 v6, 26, v6
	v_ashrrev_i32_e32 v5, 31, v4
	v_add_u32_e32 v6, v0, v6
	v_lshrrev_b32_e32 v5, 26, v5
	v_ashrrev_i32_e32 v141, 6, v6
	v_add_u32_e32 v5, v4, v5
	v_lshlrev_b32_e32 v6, 3, v141
	v_ashrrev_i32_e32 v140, 6, v5
	v_and_b32_e32 v6, -16, v6
	v_add_u32_e32 v6, v140, v6
	v_and_b32_e32 v7, 3, v140
	s_mov_b32 s0, 0x3ffe0
	s_ashr_i32 s15, s19, 31
	v_and_or_b32 v7, v6, s0, v7
	s_lshr_b32 s0, s15, 29
	s_add_i32 s0, s19, s0
	s_ashr_i32 s4, s3, 6
	s_ashr_i32 s1, s0, 3
	s_and_b32 s0, s0, -8
	s_ashr_i32 s5, s3, 8
	s_lshl_b32 s14, s4, 10
	s_sub_i32 s0, s19, s0
	s_cmp_lt_i32 s0, 0
	s_movk_i32 s2, 0xa1
	s_cselect_b32 s2, s2, 0xa0
	s_mul_i32 s0, s0, s2
	s_add_i32 s0, s0, s1
	s_ashr_i32 s1, s0, 31
	s_lshr_b32 s1, s1, 26
	s_add_i32 s1, s0, s1
	s_ashr_i32 s2, s1, 5
	s_and_b32 s1, s1, 0xffe0
	s_sub_i32 s0, s0, s1
	s_bfe_i32 s1, s0, 0x80000
	s_bfe_u32 s1, s1, 0x3000c
	s_add_i32 s1, s0, s1
	v_lshrrev_b32_e32 v8, 2, v6
	v_lshlrev_b32_e32 v9, 1, v6
	v_and_b32_e32 v5, 0xc0, v5
	s_lshl_b32 s6, s2, 2
	s_bfe_i32 s2, s1, 0x80000
	s_and_b32 s1, s1, 0xfc
	v_and_b32_e32 v8, 4, v8
	v_and_b32_e32 v9, 24, v9
	v_sub_u32_e32 v4, v4, v5
	s_sext_i32_i16 s2, s2
	s_sub_i32 s0, s0, s1
	v_or3_b32 v7, v7, v8, v9
	v_lshlrev_b32_e32 v8, 5, v141
	v_ashrrev_i16_sdwa v4, v241, sext(v4) dst_sel:DWORD dst_unused:UNUSED_PAD src0_sel:DWORD src1_sel:BYTE_0
	s_lshr_b32 s2, s2, 2
	s_sext_i32_i8 s0, s0
	v_and_b32_e32 v8, 32, v8
	v_bfe_i32 v142, v4, 0, 16
	s_add_i32 s10, s6, s0
	s_bfe_i64 s[6:7], s[2:3], 0x100000
	v_add_lshl_u32 v4, v8, v142, 1
	s_lshl_b64 s[6:7], s[6:7], 22
	v_lshl_add_u32 v192, v7, 14, v4
	v_lshl_add_u64 v[132:133], v[198:199], 0, s[6:7]
	v_mov_b32_e32 v193, v1
	s_add_i32 s16, s14, 0
	v_lshl_add_u64 v[134:135], v[132:133], 0, v[192:193]
	s_add_i32 m0, s16, 0x10000
	v_lshl_add_u32 v194, v6, 14, v4
	v_mov_b32 v124, 0
	v_mov_b32 v125, 0
	v_mov_b32 v126, 0
	v_mov_b32 v127, 0
	v_mov_b32 v128, 0
	v_mov_b32 v129, 0
	v_mov_b32 v130, 0
	v_mov_b32 v131, 0
	v_mov_b32 v112, 0
	v_mov_b32 v113, 0
	v_mov_b32 v114, 0
	v_mov_b32 v115, 0
	v_mov_b32 v108, 0
	v_mov_b32 v109, 0
	v_mov_b32 v110, 0
	v_mov_b32 v111, 0
	v_mov_b32 v96, 0
	v_mov_b32 v97, 0
	v_mov_b32 v98, 0
	v_mov_b32 v99, 0
	v_mov_b32 v92, 0
	v_mov_b32 v93, 0
	v_mov_b32 v94, 0
	v_mov_b32 v95, 0
	v_mov_b32 v80, 0
	v_mov_b32 v81, 0
	v_mov_b32 v82, 0
	v_mov_b32 v83, 0
	v_mov_b32 v76, 0
	v_mov_b32 v77, 0
	v_mov_b32 v78, 0
	v_mov_b32 v79, 0
	v_mov_b32 v120, 0
	v_mov_b32 v121, 0
	v_mov_b32 v122, 0
	v_mov_b32 v123, 0
	v_mov_b32 v116, 0
	v_mov_b32 v117, 0
	v_mov_b32 v118, 0
	v_mov_b32 v119, 0
	v_mov_b32 v104, 0
	v_mov_b32 v105, 0
	v_mov_b32 v106, 0
	v_mov_b32 v107, 0
	v_mov_b32 v100, 0
	v_mov_b32 v101, 0
	v_mov_b32 v102, 0
	v_mov_b32 v103, 0
	v_mov_b32 v88, 0
	v_mov_b32 v89, 0
	v_mov_b32 v90, 0
	v_mov_b32 v91, 0
	v_mov_b32 v84, 0
	v_mov_b32 v85, 0
	v_mov_b32 v86, 0
	v_mov_b32 v87, 0
	v_mov_b32 v72, 0
	v_mov_b32 v73, 0
	v_mov_b32 v74, 0
	v_mov_b32 v75, 0
	v_mov_b32 v68, 0
	v_mov_b32 v69, 0
	v_mov_b32 v70, 0
	v_mov_b32 v71, 0
	v_mov_b32 v64, 0
	v_mov_b32 v65, 0
	v_mov_b32 v66, 0
	v_mov_b32 v67, 0
	v_mov_b32 v60, 0
	v_mov_b32 v61, 0
	v_mov_b32 v62, 0
	v_mov_b32 v63, 0
	v_mov_b32 v48, 0
	v_mov_b32 v49, 0
	v_mov_b32 v50, 0
	v_mov_b32 v51, 0
	v_mov_b32 v44, 0
	v_mov_b32 v45, 0
	v_mov_b32 v46, 0
	v_mov_b32 v47, 0
	v_mov_b32 v32, 0
	v_mov_b32 v33, 0
	v_mov_b32 v34, 0
	v_mov_b32 v35, 0
	v_mov_b32 v28, 0
	v_mov_b32 v29, 0
	v_mov_b32 v30, 0
	v_mov_b32 v31, 0
	v_mov_b32 v16, 0
	v_mov_b32 v17, 0
	v_mov_b32 v18, 0
	v_mov_b32 v19, 0
	v_mov_b32 v12, 0
	v_mov_b32 v13, 0
	v_mov_b32 v14, 0
	v_mov_b32 v15, 0
	v_mov_b32 v56, 0
	v_mov_b32 v57, 0
	v_mov_b32 v58, 0
	v_mov_b32 v59, 0
	v_mov_b32 v52, 0
	v_mov_b32 v53, 0
	v_mov_b32 v54, 0
	v_mov_b32 v55, 0
	v_mov_b32 v40, 0
	v_mov_b32 v41, 0
	v_mov_b32 v42, 0
	v_mov_b32 v43, 0
	v_mov_b32 v36, 0
	v_mov_b32 v37, 0
	v_mov_b32 v38, 0
	v_mov_b32 v39, 0
	v_mov_b32 v24, 0
	v_mov_b32 v25, 0
	v_mov_b32 v26, 0
	v_mov_b32 v27, 0
	v_mov_b32 v20, 0
	v_mov_b32 v21, 0
	v_mov_b32 v22, 0
	v_mov_b32 v23, 0
	v_mov_b32 v8, 0
	v_mov_b32 v9, 0
	v_mov_b32 v10, 0
	v_mov_b32 v11, 0
	v_mov_b32 v4, 0
	v_mov_b32 v5, 0
	v_mov_b32 v6, 0
	v_mov_b32 v7, 0
	s_ashr_i32 s11, s10, 31
	global_load_lds_dwordx4 v[134:135], off
	v_lshl_add_u64 v[136:137], v[134:135], 0, s[84:85]
	s_add_i32 m0, s16, 0x12000
	s_lshl_b64 s[0:1], s[10:11], 22
	global_load_lds_dwordx4 v[136:137], off
	v_lshl_add_u64 v[136:137], v[134:135], 0, s[50:51]
	s_add_i32 m0, s16, 0x14000
	v_lshl_add_u64 v[138:139], v[202:203], 0, s[0:1]
	global_load_lds_dwordx4 v[136:137], off
	v_lshl_add_u64 v[136:137], v[134:135], 0, s[94:95]
	s_add_i32 m0, s16, 0x16000
	v_mov_b32_e32 v195, v1
	global_load_lds_dwordx4 v[136:137], off
	v_lshl_add_u64 v[136:137], v[138:139], 0, v[194:195]
	s_mov_b32 m0, s16
	s_add_i32 s17, s16, 0x2000
	global_load_lds_dwordx4 v[136:137], off
	v_lshl_add_u64 v[144:145], v[136:137], 0, s[84:85]
	s_mov_b32 m0, s17
	s_add_i32 s20, s16, 0x4000
	global_load_lds_dwordx4 v[144:145], off
	v_lshl_add_u64 v[144:145], v[136:137], 0, s[50:51]
	s_mov_b32 m0, s20
	s_add_i32 s21, s16, 0x6000
	global_load_lds_dwordx4 v[144:145], off
	v_lshl_add_u64 v[144:145], v[136:137], 0, s[94:95]
	s_mov_b32 m0, s21
	s_cmp_eq_u32 s5, 1
	global_load_lds_dwordx4 v[144:145], off
	s_cselect_b64 s[0:1], -1, 0
	s_cmp_lg_u32 s5, 1
	s_cbranch_scc1 .LBB0_1262
	s_barrier

.LBB0_1265:
	s_add_i32 s25, s25, 1
	s_mul_i32 s4, s25, s24
	s_mul_hi_u32 s5, s25, s18
	s_add_i32 s5, s5, s4
	s_mul_i32 s4, s25, s18
	s_add_u32 s12, s4, s19
	s_addc_u32 s13, s5, s15
	v_mov_b64_e32 v[134:135], 0x4ff
	v_cmp_gt_i64_e32 vcc, s[12:13], v[134:135]
	v_mov_b64_e32 v[252:253], 0x500
	v_cmp_lt_i64_e64 s[4:5], s[12:13], v[242:243]
	s_cbranch_vccnz .LBB0_1267
	s_ashr_i32 s6, s12, 31
	s_lshr_b32 s6, s6, 29
	s_add_i32 s6, s12, s6
	s_ashr_i32 s7, s6, 3
	s_and_b32 s6, s6, -8
	s_sub_i32 s6, s12, s6
	s_cmp_lt_i32 s6, 0
	s_movk_i32 s8, 0xa1
	s_cselect_b32 s8, s8, 0xa0
	s_mul_i32 s6, s6, s8
	s_add_i32 s6, s6, s7
	s_ashr_i32 s7, s6, 31
	s_lshr_b32 s7, s7, 26
	s_add_i32 s7, s6, s7
	s_ashr_i32 s8, s7, 5
	s_lshl_b32 s8, s8, 2
	s_sub_i32 s9, 0xa0, s8
	s_min_i32 s9, s9, 4
	s_abs_i32 s12, s9
	v_cvt_f32_u32_e32 v0, s12
	s_sub_i32 s26, 0, s12
	s_andn2_b32 s7, s7, 31
	s_sub_i32 s7, s6, s7
	v_rcp_iflag_f32_e32 v0, v0
	s_abs_i32 s6, s7
	s_xor_b32 s13, s7, s9
	s_ashr_i32 s13, s13, 31
	v_mul_f32_e32 v0, 0x4f7ffffe, v0
	v_cvt_u32_f32_e32 v0, v0
	s_nop 0
	v_readfirstlane_b32 s27, v0
	s_mul_i32 s26, s26, s27
	s_mul_hi_u32 s26, s27, s26
	s_add_i32 s27, s27, s26
	s_mul_hi_u32 s26, s6, s27
	s_mul_i32 s27, s26, s12
	s_sub_i32 s6, s6, s27
	s_add_i32 s28, s26, 1
	s_sub_i32 s27, s6, s12
	s_cmp_ge_u32 s6, s12
	s_cselect_b32 s26, s28, s26
	s_cselect_b32 s6, s27, s6
	s_add_i32 s27, s26, 1
	s_cmp_ge_u32 s6, s12
	s_cselect_b32 s6, s27, s26
	s_xor_b32 s6, s6, s13
	s_sub_i32 s6, s6, s13
	s_mul_i32 s9, s6, s9
	s_sub_i32 s7, s7, s9
	s_add_i32 s8, s8, s7
